# P2: prefetch next tile SA(1,1) before epilogue, peeled iteration 0 without its first three DMA waits so the epilogue store drain overlaps MFMA work
# speedup vs baseline: 1.0067x; 1.0067x over previous
; #define PG8_STAGE(bufoff, gbase, voff) do { _Pragma("unroll") for (int _i = 0; _i < 2; ++_i) \
;         __builtin_amdgcn_global_load_lds((const unsigned*)((const char*)(gbase) + (voff)[_i]), (PG8_LAS unsigned*)(lds + (bufoff) + ldsw + _i * 8192), 16, 0, 0); } while (0)
; #define PG8_WAIT_V(n) asm volatile("s_waitcnt vmcnt(" #n ")" ::: "memory")
; #define PG8_BAR __builtin_amdgcn_s_barrier()
; template <class Epi, class Sched, bool ALIGN_EPI = false, bool SP2 = false>
; __device__ __forceinline__ void gemm_phase(PG8_LAS unsigned char* lds, const Gemm g, const Sched& S, const Epi& E) {
;     ...
;     for (int i = 0; i < 2; ++i) { int R, C; stage_rc(tid * 16 + i * 8192, R, C); const int Rb = Epi::PERM ? ((R & ~31) + perm32(R & 31)) : R;
;         voffA[i] = (unsigned)(R * K + C) * 2u; voffB[i] = (unsigned)(Rb * K + C) * 2u; }
;     const size_t kstep = (size_t)(BK * 2);
;     const size_t hstep = (size_t)HALF * K * 2;
;     const size_t tstep = 2 * hstep;
;     const unsigned ldsw = (unsigned)wid * 1024u;
;     const int aoff = lds_byte(wr * 64 + fr, fq * 8), boff = lds_byte(wc * 32 + fr, fq * 8);
;     ...
;     if constexpr (SP2) {
;         PG8_STAGE(PG8_SB(0, 0), cB, voffB); PG8_STAGE(PG8_SB(0, 1), cB + hstep, voffB); PG8_STAGE(PG8_SA(0, 0), cA, voffA); PG8_STAGE(PG8_SA(0, 1), cA + hstep, voffA);
;         if (wr == 1) PG8_BAR;
;         PG8_WAIT_V(2); PG8_BAR;
;         PG8_STAGE(PG8_SB(1, 0), cB + kstep, voffB); PG8_STAGE(PG8_SA(1, 0), cA + kstep, voffA); PG8_STAGE(PG8_SB(1, 1), cB + hstep + kstep, voffB);
;         PG8_WAIT_V(6); PG8_BAR;
.LBB0_194:
	s_lshl_b32 s12, s12, 5
	s_and_b32 s38, s12, 0x60
	s_mov_b64 s[12:13], 0x80
	s_add_i32 m0, s33, 0x18000
	v_lshl_add_u64 v[6:7], v[6:7], 0, s[12:13]
	s_lshl_b32 s15, s14, 13
	s_lshl_b32 s39, s38, 7
	s_waitcnt vmcnt(2)
	s_barrier
	global_load_lds_dwordx4 v[6:7], off
	v_lshl_add_u64 v[2:3], v[2:3], 0, s[12:13]
	s_add_i32 m0, s33, 0x1a000
	s_add_i32 s80, s33, 0x8000
	s_add_i32 s81, s33, 0xa000
	global_load_lds_dwordx4 v[2:3], off
	v_lshl_add_u64 v[0:1], v[0:1], 0, s[12:13]
	s_mov_b32 m0, s80
	s_add_u32 s34, s72, 0x80080
	global_load_lds_dwordx4 v[0:1], off
	v_lshl_add_u64 v[0:1], v[4:5], 0, s[12:13]
	s_mov_b32 m0, s81
	s_addc_u32 s35, s73, 0
	global_load_lds_dwordx4 v[0:1], off
	s_add_i32 m0, s33, 0x1c000
	v_lshl_add_u64 v[0:1], s[34:35], 0, v[132:133]
	global_load_lds_dwordx4 v[0:1], off
	v_lshl_add_u64 v[0:1], s[34:35], 0, v[128:129]
	s_add_i32 m0, s33, 0x1e000
	s_sext_i32_i16 s89, s0
	global_load_lds_dwordx4 v[0:1], off
	v_and_b32_e32 v0, 15, v146
	v_lshlrev_b32_e32 v1, 1, v11
	v_lshlrev_b32_e32 v2, 2, v146
	v_lshlrev_b32_e32 v3, 6, v146
	s_movk_i32 s0, 0x3c0
	v_lshl_or_b32 v160, s14, 6, v0
	v_lshl_or_b32 v0, v0, 6, v1
	v_and_b32_e32 v2, 32, v2
	v_and_or_b32 v1, v3, s0, v1
	v_bitop3_b32 v161, s39, v1, v2 bitop3:0xf6
	v_lshlrev_b32_e32 v1, 9, v146
	v_bitop3_b32 v0, v0, s15, v2 bitop3:0xde
	v_and_b32_e32 v1, 0x70000, v1
	v_lshlrev_b32_e32 v2, 12, v12
	v_or3_b32 v1, v9, v1, v2
	v_add_u32_e32 v138, v1, v10
	v_lshlrev_b32_e32 v1, 5, v8
	s_waitcnt vmcnt(6)
	s_cmpk_lt_u32 s1, 0x100
	v_and_b32_e32 v1, 0xf0000, v1
	v_or_b32_e32 v162, s38, v11
	s_cselect_b64 s[14:15], -1, 0
	v_or3_b32 v1, v9, v1, v2
	s_add_i32 s84, 0, 0x10000
	s_add_i32 s85, 0, 0x14000
	v_or_b32_e32 v163, 0xfffffc00, v162
	s_ashr_i32 s82, s18, 31
	s_mov_b32 s83, s18
	v_mov_b32_e32 v139, v137
	v_add_u32_e32 v140, v1, v10
	v_mov_b32_e32 v141, v137
	v_mov_b64_e32 v[142:143], 0x6c0
	v_mov_b64_e32 v[144:145], 0x6bf
	v_add_u32_e32 v164, s84, v161
	v_add_u32_e32 v165, s85, v161
	v_add_u32_e32 v166, 0, v0
	s_mov_b32 s86, 0x80000
	s_mov_b32 s87, 0x90000
	s_mov_b32 s88, 0xa0000
	s_add_u32 s100, s70, 0x80080
	s_addc_u32 s101, s71, 0
	v_lshl_add_u64 v[220:221], s[100:101], 0, v[138:139]
	s_add_i32 m0, s33, 0xc000
	s_nop 0
	global_load_lds_dwordx4 v[220:221], off
	v_lshl_add_u64 v[220:221], s[100:101], 0, v[140:141]
	s_add_i32 m0, s33, 0xe000
	s_nop 0
	global_load_lds_dwordx4 v[220:221], off
	s_waitcnt vmcnt(0)
	s_barrier
	s_branch .LBB0_197

;     __host__ __device__ bool next(int i, Unit& u) const { return map((long)i * G + c, u); }
; #define PG8_STAGE(bufoff, gbase, voff) do { _Pragma("unroll") for (int _i = 0; _i < 2; ++_i) \
;         __builtin_amdgcn_global_load_lds((const unsigned*)((const char*)(gbase) + (voff)[_i]), (PG8_LAS unsigned*)(lds + (bufoff) + ldsw + _i * 8192), 16, 0, 0); } while (0)
; #define PG8_LDA(dst, b, h) do { _Pragma("unroll") for (int m = 0; m < 4; ++m) _Pragma("unroll") for (int k = 0; k < 2; ++k) dst[m][k] = *(const PG8_LAS bf16x8*)(lds + PG8_SA(b, h) + aoff + m * 2048 + k * 1024); } while (0)
; #define PG8_LDB(dst, b, h) do { _Pragma("unroll") for (int n = 0; n < 2; ++n) _Pragma("unroll") for (int k = 0; k < 2; ++k) dst[n][k] = *(const PG8_LAS bf16x8*)(lds + PG8_SB(b, h) + boff + n * 2048 + k * 1024); } while (0)
; #define PG8_MMA(ai, bj, At, Bt) do { __builtin_amdgcn_s_setprio(1); _Pragma("unroll") for (int m = 0; m < 4; ++m) _Pragma("unroll") for (int n = 0; n < 2; ++n) _Pragma("unroll") for (int k = 0; k < 2; ++k) \
;         acc[ai][bj][m][n] = __builtin_amdgcn_mfma_f32_16x16x32_bf16(Bt[n][k], At[m][k], acc[ai][bj][m][n], 0, 0, 0); __builtin_amdgcn_s_setprio(0); } while (0)
; #define PG8_WAIT_V(n) asm volatile("s_waitcnt vmcnt(" #n ")" ::: "memory")
; #define PG8_WAIT_L(n) asm volatile("s_waitcnt lgkmcnt(" #n ")" ::: "memory")
; #define PG8_BAR __builtin_amdgcn_s_barrier()
; #define PG8_SCHED __builtin_amdgcn_sched_barrier(0)
; template <class Epi, class Sched, bool ALIGN_EPI = false, bool SP2 = false>
; __device__ __forceinline__ void gemm_phase(PG8_LAS unsigned char* lds, const Gemm g, const Sched& S, const Epi& E) {
;     ...
;         const bool has_next = S.next(ui + 1, nxt);
;         const char* nA = has_next ? PG8_UA(nxt) : cA; const char* nB = has_next ? PG8_UB(nxt) : cB;
;     ...
;             PG8_LDB(B0, 0, 0); PG8_LDB(B1, 0, 1); PG8_SCHED; PG8_LDA(At, 0, 0); PG8_STAGE(PG8_SA(1, 1), a1 + hstep, voffA);
;             PG8_WAIT_V(8); PG8_WAIT_L(0); PG8_BAR; PG8_MMA(0, 0, At, B0); PG8_MMA(0, 1, At, B1); PG8_BAR; PG8_SCHED;
;     ...
; #pragma unroll
;         for (int a = 0; a < 2; ++a)
; #pragma unroll
;             for (int b = 0; b < 2; ++b)
; #pragma unroll
;                 for (int m = 0; m < 4; ++m)
; #pragma unroll
;                     for (int n = 0; n < 2; ++n) acc[a][b][m][n] = (f32x4){0.f, 0.f, 0.f, 0.f};
;         cur = nxt; cA = nA; cB = nB; ++ui;
.LBB0_199:
	s_ashr_i32 s39, s38, 31
	s_lshl_b64 s[48:49], s[38:39], 20
	s_add_u32 s48, s30, s48
	s_addc_u32 s49, s31, s49
	s_and_b64 s[50:51], s[0:1], exec
	s_cselect_b32 s39, s49, s71
	s_cselect_b32 s69, s48, s70
	s_ashr_i32 s35, s34, 31
	s_lshl_b64 s[50:51], s[34:35], 20
	s_add_u32 s50, s8, s50
	s_addc_u32 s51, s9, s51
	s_and_b64 s[74:75], s[0:1], exec
	s_cselect_b32 s35, s51, s73
	s_cselect_b32 s90, s50, s72
	s_add_u32 s70, s70, 0x80080
	s_addc_u32 s71, s71, 0
	s_add_u32 s91, s72, 0x100
	v_mov_b32_e32 v0, 0
	s_addc_u32 s92, s73, 0
	s_mov_b32 s93, -2
	v_mov_b32_e32 v1, v0
	v_mov_b32_e32 v2, v0
	v_mov_b32_e32 v3, v0
	v_mov_b32_e32 v4, v0
	v_mov_b32_e32 v5, v0
	v_mov_b32_e32 v6, v0
	v_mov_b32_e32 v7, v0
	v_mov_b32_e32 v8, v0
	v_mov_b32_e32 v9, v0
	v_mov_b32_e32 v10, v0
	v_mov_b32_e32 v11, v0
	v_mov_b32_e32 v16, v0
	v_mov_b32_e32 v17, v0
	v_mov_b32_e32 v18, v0
	v_mov_b32_e32 v19, v0
	v_mov_b32_e32 v24, v0
	v_mov_b32_e32 v25, v0
	v_mov_b32_e32 v26, v0
	v_mov_b32_e32 v27, v0
	v_mov_b32_e32 v32, v0
	v_mov_b32_e32 v33, v0
	v_mov_b32_e32 v34, v0
	v_mov_b32_e32 v35, v0
	v_mov_b32_e32 v40, v0
	v_mov_b32_e32 v41, v0
	v_mov_b32_e32 v42, v0
	v_mov_b32_e32 v43, v0
	v_mov_b32_e32 v48, v0
	v_mov_b32_e32 v49, v0
	v_mov_b32_e32 v50, v0
	v_mov_b32_e32 v51, v0
	v_mov_b32_e32 v12, v0
	v_mov_b32_e32 v13, v0
	v_mov_b32_e32 v14, v0
	v_mov_b32_e32 v15, v0
	v_mov_b32_e32 v20, v0
	v_mov_b32_e32 v21, v0
	v_mov_b32_e32 v22, v0
	v_mov_b32_e32 v23, v0
	v_mov_b32_e32 v28, v0
	v_mov_b32_e32 v29, v0
	v_mov_b32_e32 v30, v0
	v_mov_b32_e32 v31, v0
	v_mov_b32_e32 v36, v0
	v_mov_b32_e32 v37, v0
	v_mov_b32_e32 v38, v0
	v_mov_b32_e32 v39, v0
	v_mov_b32_e32 v44, v0
	v_mov_b32_e32 v45, v0
	v_mov_b32_e32 v46, v0
	v_mov_b32_e32 v47, v0
	v_mov_b32_e32 v52, v0
	v_mov_b32_e32 v53, v0
	v_mov_b32_e32 v54, v0
	v_mov_b32_e32 v55, v0
	v_mov_b32_e32 v56, v0
	v_mov_b32_e32 v57, v0
	v_mov_b32_e32 v58, v0
	v_mov_b32_e32 v59, v0
	v_mov_b32_e32 v60, v0
	v_mov_b32_e32 v61, v0
	v_mov_b32_e32 v62, v0
	v_mov_b32_e32 v63, v0
	v_mov_b32_e32 v64, v0
	v_mov_b32_e32 v65, v0
	v_mov_b32_e32 v66, v0
	v_mov_b32_e32 v67, v0
	v_mov_b32_e32 v68, v0
	v_mov_b32_e32 v69, v0
	v_mov_b32_e32 v70, v0
	v_mov_b32_e32 v71, v0
	v_mov_b32_e32 v72, v0
	v_mov_b32_e32 v73, v0
	v_mov_b32_e32 v74, v0
	v_mov_b32_e32 v75, v0
	v_mov_b32_e32 v80, v0
	v_mov_b32_e32 v81, v0
	v_mov_b32_e32 v82, v0
	v_mov_b32_e32 v83, v0
	v_mov_b32_e32 v88, v0
	v_mov_b32_e32 v89, v0
	v_mov_b32_e32 v90, v0
	v_mov_b32_e32 v91, v0
	v_mov_b32_e32 v96, v0
	v_mov_b32_e32 v97, v0
	v_mov_b32_e32 v98, v0
	v_mov_b32_e32 v99, v0
	v_mov_b32_e32 v104, v0
	v_mov_b32_e32 v105, v0
	v_mov_b32_e32 v106, v0
	v_mov_b32_e32 v107, v0
	v_mov_b32_e32 v112, v0
	v_mov_b32_e32 v113, v0
	v_mov_b32_e32 v114, v0
	v_mov_b32_e32 v115, v0
	v_mov_b32_e32 v76, v0
	v_mov_b32_e32 v77, v0
	v_mov_b32_e32 v78, v0
	v_mov_b32_e32 v79, v0
	v_mov_b32_e32 v84, v0
	v_mov_b32_e32 v85, v0
	v_mov_b32_e32 v86, v0
	v_mov_b32_e32 v87, v0
	v_mov_b32_e32 v92, v0
	v_mov_b32_e32 v93, v0
	v_mov_b32_e32 v94, v0
	v_mov_b32_e32 v95, v0
	v_mov_b32_e32 v100, v0
	v_mov_b32_e32 v101, v0
	v_mov_b32_e32 v102, v0
	v_mov_b32_e32 v103, v0
	v_mov_b32_e32 v108, v0
	v_mov_b32_e32 v109, v0
	v_mov_b32_e32 v110, v0
	v_mov_b32_e32 v111, v0
	v_mov_b32_e32 v116, v0
	v_mov_b32_e32 v117, v0
	v_mov_b32_e32 v118, v0
	v_mov_b32_e32 v119, v0
	v_mov_b32_e32 v120, v0
	v_mov_b32_e32 v121, v0
	v_mov_b32_e32 v122, v0
	v_mov_b32_e32 v123, v0
	v_mov_b32_e32 v124, v0
	v_mov_b32_e32 v125, v0
	v_mov_b32_e32 v126, v0
	v_mov_b32_e32 v127, v0
	ds_read_b128 v[148:151], v164
	ds_read_b128 v[152:155], v164 offset:1024
	ds_read_b128 v[156:159], v164 offset:2048
	ds_read_b128 v[168:171], v164 offset:3072
	ds_read_b128 v[172:175], v165
	ds_read_b128 v[176:179], v165 offset:1024
	ds_read_b128 v[180:183], v165 offset:2048
	ds_read_b128 v[184:187], v165 offset:3072
	s_add_u32 s52, s70, 0xfff80080
	s_addc_u32 s53, s71, -1
	s_cmp_eq_u32 s93, 28
	s_cselect_b32 s75, s39, s53
	s_cselect_b32 s74, s69, s52
	s_cselect_b32 s73, s35, s92
	s_cselect_b32 s72, s90, s91
	v_lshl_add_u64 v[220:221], s[70:71], 0, v[138:139]
	s_add_i32 m0, s33, 0xc000
	ds_read_b128 v[188:191], v166
	ds_read_b128 v[192:195], v166 offset:1024
	ds_read_b128 v[196:199], v166 offset:2048
	ds_read_b128 v[200:203], v166 offset:3072
	ds_read_b128 v[204:207], v166 offset:4096
	ds_read_b128 v[208:211], v166 offset:5120
	ds_read_b128 v[212:215], v166 offset:6144
	ds_read_b128 v[216:219], v166 offset:7168
	v_lshl_add_u64 v[220:221], s[70:71], 0, v[140:141]
	s_add_i32 m0, s33, 0xe000
	s_nop 0
	s_waitcnt lgkmcnt(0)
	s_barrier
; #define PG8_STAGE(bufoff, gbase, voff) do { _Pragma("unroll") for (int _i = 0; _i < 2; ++_i) \
;         __builtin_amdgcn_global_load_lds((const unsigned*)((const char*)(gbase) + (voff)[_i]), (PG8_LAS unsigned*)(lds + (bufoff) + ldsw + _i * 8192), 16, 0, 0); } while (0)
; #define PG8_LDA(dst, b, h) do { _Pragma("unroll") for (int m = 0; m < 4; ++m) _Pragma("unroll") for (int k = 0; k < 2; ++k) dst[m][k] = *(const PG8_LAS bf16x8*)(lds + PG8_SA(b, h) + aoff + m * 2048 + k * 1024); } while (0)
; #define PG8_LDB(dst, b, h) do { _Pragma("unroll") for (int n = 0; n < 2; ++n) _Pragma("unroll") for (int k = 0; k < 2; ++k) dst[n][k] = *(const PG8_LAS bf16x8*)(lds + PG8_SB(b, h) + boff + n * 2048 + k * 1024); } while (0)
; #define PG8_MMA(ai, bj, At, Bt) do { __builtin_amdgcn_s_setprio(1); _Pragma("unroll") for (int m = 0; m < 4; ++m) _Pragma("unroll") for (int n = 0; n < 2; ++n) _Pragma("unroll") for (int k = 0; k < 2; ++k) \
;         acc[ai][bj][m][n] = __builtin_amdgcn_mfma_f32_16x16x32_bf16(Bt[n][k], At[m][k], acc[ai][bj][m][n], 0, 0, 0); __builtin_amdgcn_s_setprio(0); } while (0)
; #define PG8_WAIT_V(n) asm volatile("s_waitcnt vmcnt(" #n ")" ::: "memory")
; #define PG8_WAIT_L(n) asm volatile("s_waitcnt lgkmcnt(" #n ")" ::: "memory")
; #define PG8_BAR __builtin_amdgcn_s_barrier()
; #define PG8_SCHED __builtin_amdgcn_sched_barrier(0)
; template <class Epi, class Sched, bool ALIGN_EPI = false, bool SP2 = false>
; __device__ __forceinline__ void gemm_phase(PG8_LAS unsigned char* lds, const Gemm g, const Sched& S, const Epi& E) {
;     ...
;             PG8_LDB(B0, 0, 0); PG8_LDB(B1, 0, 1); PG8_SCHED; PG8_LDA(At, 0, 0); PG8_STAGE(PG8_SA(1, 1), a1 + hstep, voffA);
;             PG8_WAIT_V(8); PG8_WAIT_L(0); PG8_BAR; PG8_MMA(0, 0, At, B0); PG8_MMA(0, 1, At, B1); PG8_BAR; PG8_SCHED;
;             PG8_LDA(At, 0, 1); PG8_STAGE(PG8_SB(0, 0), b2, voffB); PG8_STAGE(PG8_SB(0, 1), b2 + hstep, voffB); PG8_STAGE(PG8_SA(0, 0), a2, voffA);
;             PG8_WAIT_V(8); PG8_WAIT_L(0); PG8_BAR; PG8_MMA(1, 0, At, B0); PG8_MMA(1, 1, At, B1); PG8_BAR; PG8_SCHED;
	s_setprio 1
	s_waitcnt lgkmcnt(0)
	v_mfma_f32_16x16x32_bf16 v[124:127], v[148:151], v[188:191], v[124:127]
	v_mfma_f32_16x16x32_bf16 v[120:123], v[156:159], v[188:191], v[120:123]
	v_mfma_f32_16x16x32_bf16 v[116:119], v[148:151], v[196:199], v[116:119]
	v_mfma_f32_16x16x32_bf16 v[108:111], v[156:159], v[196:199], v[108:111]
	v_mfma_f32_16x16x32_bf16 v[100:103], v[148:151], v[204:207], v[100:103]
	v_mfma_f32_16x16x32_bf16 v[92:95], v[156:159], v[204:207], v[92:95]
	v_mfma_f32_16x16x32_bf16 v[84:87], v[148:151], v[212:215], v[84:87]
	v_mfma_f32_16x16x32_bf16 v[76:79], v[156:159], v[212:215], v[76:79]
	v_mfma_f32_16x16x32_bf16 v[124:127], v[152:155], v[192:195], v[124:127]
	v_mfma_f32_16x16x32_bf16 v[120:123], v[168:171], v[192:195], v[120:123]
	v_mfma_f32_16x16x32_bf16 v[116:119], v[152:155], v[200:203], v[116:119]
	v_mfma_f32_16x16x32_bf16 v[108:111], v[168:171], v[200:203], v[108:111]
	v_mfma_f32_16x16x32_bf16 v[100:103], v[152:155], v[208:211], v[100:103]
	v_mfma_f32_16x16x32_bf16 v[92:95], v[168:171], v[208:211], v[92:95]
	v_mfma_f32_16x16x32_bf16 v[84:87], v[152:155], v[216:219], v[84:87]
	v_mfma_f32_16x16x32_bf16 v[76:79], v[168:171], v[216:219], v[76:79]
	s_setprio 0
	s_setprio 1
	v_mfma_f32_16x16x32_bf16 v[112:115], v[172:175], v[188:191], v[112:115]
	v_mfma_f32_16x16x32_bf16 v[104:107], v[180:183], v[188:191], v[104:107]
	v_mfma_f32_16x16x32_bf16 v[96:99], v[172:175], v[196:199], v[96:99]
	v_mfma_f32_16x16x32_bf16 v[88:91], v[180:183], v[196:199], v[88:91]
	v_mfma_f32_16x16x32_bf16 v[80:83], v[172:175], v[204:207], v[80:83]
	v_mfma_f32_16x16x32_bf16 v[72:75], v[180:183], v[204:207], v[72:75]
	v_mfma_f32_16x16x32_bf16 v[68:71], v[172:175], v[212:215], v[68:71]
	v_mfma_f32_16x16x32_bf16 v[64:67], v[180:183], v[212:215], v[64:67]
	v_mfma_f32_16x16x32_bf16 v[112:115], v[176:179], v[192:195], v[112:115]
	v_mfma_f32_16x16x32_bf16 v[104:107], v[184:187], v[192:195], v[104:107]
	v_mfma_f32_16x16x32_bf16 v[96:99], v[176:179], v[200:203], v[96:99]
	v_mfma_f32_16x16x32_bf16 v[88:91], v[184:187], v[200:203], v[88:91]
	v_mfma_f32_16x16x32_bf16 v[80:83], v[176:179], v[208:211], v[80:83]
	v_mfma_f32_16x16x32_bf16 v[72:75], v[184:187], v[208:211], v[72:75]
	v_mfma_f32_16x16x32_bf16 v[68:71], v[176:179], v[216:219], v[68:71]
	v_mfma_f32_16x16x32_bf16 v[64:67], v[184:187], v[216:219], v[64:67]
	s_setprio 0
	s_barrier
	s_add_i32 s52, s84, s3
	v_lshl_add_u64 v[220:221], s[72:73], 0, v[132:133]
	s_mov_b32 m0, s52
	ds_read_b128 v[188:191], v166 offset:16384
	ds_read_b128 v[192:195], v166 offset:17408
	ds_read_b128 v[196:199], v166 offset:18432
	ds_read_b128 v[200:203], v166 offset:19456
	ds_read_b128 v[204:207], v166 offset:20480
	ds_read_b128 v[208:211], v166 offset:21504
	ds_read_b128 v[212:215], v166 offset:22528
	ds_read_b128 v[216:219], v166 offset:23552
	global_load_lds_dwordx4 v[220:221], off
	s_add_i32 m0, s52, 0x2000
	s_add_u32 s96, s72, 0x80000
	v_lshl_add_u64 v[222:223], s[72:73], 0, v[128:129]
	s_addc_u32 s97, s73, 0
	s_add_i32 s52, s85, s3
	global_load_lds_dwordx4 v[222:223], off
	v_lshl_add_u64 v[224:225], s[96:97], 0, v[132:133]
	s_mov_b32 m0, s52
	v_lshl_add_u64 v[226:227], s[74:75], 0, v[130:131]
	global_load_lds_dwordx4 v[224:225], off
	v_lshl_add_u64 v[224:225], s[96:97], 0, v[128:129]
	s_add_i32 m0, s52, 0x2000
	s_nop 0
	global_load_lds_dwordx4 v[224:225], off
	v_lshl_add_u64 v[224:225], s[74:75], 0, v[134:135]
	s_mov_b32 m0, s33
	s_nop 0
	global_load_lds_dwordx4 v[224:225], off
	s_mov_b32 m0, s76
	s_nop 0
	global_load_lds_dwordx4 v[226:227], off
	s_waitcnt lgkmcnt(0)
	s_barrier
	s_setprio 1
	s_waitcnt lgkmcnt(0)
	v_mfma_f32_16x16x32_bf16 v[60:63], v[148:151], v[188:191], v[60:63]
	v_mfma_f32_16x16x32_bf16 v[56:59], v[156:159], v[188:191], v[56:59]
	v_mfma_f32_16x16x32_bf16 v[52:55], v[148:151], v[196:199], v[52:55]
	v_mfma_f32_16x16x32_bf16 v[44:47], v[156:159], v[196:199], v[44:47]
	v_mfma_f32_16x16x32_bf16 v[36:39], v[148:151], v[204:207], v[36:39]
	v_mfma_f32_16x16x32_bf16 v[28:31], v[156:159], v[204:207], v[28:31]
	v_mfma_f32_16x16x32_bf16 v[20:23], v[148:151], v[212:215], v[20:23]
	v_mfma_f32_16x16x32_bf16 v[12:15], v[156:159], v[212:215], v[12:15]
	v_mfma_f32_16x16x32_bf16 v[60:63], v[152:155], v[192:195], v[60:63]
	v_mfma_f32_16x16x32_bf16 v[56:59], v[168:171], v[192:195], v[56:59]
	v_mfma_f32_16x16x32_bf16 v[52:55], v[152:155], v[200:203], v[52:55]
	v_mfma_f32_16x16x32_bf16 v[44:47], v[168:171], v[200:203], v[44:47]
	v_mfma_f32_16x16x32_bf16 v[36:39], v[152:155], v[208:211], v[36:39]
	v_mfma_f32_16x16x32_bf16 v[28:31], v[168:171], v[208:211], v[28:31]
	v_mfma_f32_16x16x32_bf16 v[20:23], v[152:155], v[216:219], v[20:23]
	v_mfma_f32_16x16x32_bf16 v[12:15], v[168:171], v[216:219], v[12:15]
	s_setprio 0
	s_setprio 1
	v_mfma_f32_16x16x32_bf16 v[48:51], v[172:175], v[188:191], v[48:51]
	v_mfma_f32_16x16x32_bf16 v[40:43], v[180:183], v[188:191], v[40:43]
	v_mfma_f32_16x16x32_bf16 v[32:35], v[172:175], v[196:199], v[32:35]
	v_mfma_f32_16x16x32_bf16 v[24:27], v[180:183], v[196:199], v[24:27]
	v_mfma_f32_16x16x32_bf16 v[16:19], v[172:175], v[204:207], v[16:19]
	v_mfma_f32_16x16x32_bf16 v[8:11], v[180:183], v[204:207], v[8:11]
	v_mfma_f32_16x16x32_bf16 v[4:7], v[172:175], v[212:215], v[4:7]
	v_mfma_f32_16x16x32_bf16 v[0:3], v[180:183], v[212:215], v[0:3]
	v_mfma_f32_16x16x32_bf16 v[48:51], v[176:179], v[192:195], v[48:51]
	v_mfma_f32_16x16x32_bf16 v[40:43], v[184:187], v[192:195], v[40:43]
	v_mfma_f32_16x16x32_bf16 v[32:35], v[176:179], v[200:203], v[32:35]
	v_mfma_f32_16x16x32_bf16 v[24:27], v[184:187], v[200:203], v[24:27]
	v_mfma_f32_16x16x32_bf16 v[16:19], v[176:179], v[208:211], v[16:19]
	v_mfma_f32_16x16x32_bf16 v[8:11], v[184:187], v[208:211], v[8:11]
	v_mfma_f32_16x16x32_bf16 v[4:7], v[176:179], v[216:219], v[4:7]
	v_mfma_f32_16x16x32_bf16 v[0:3], v[184:187], v[216:219], v[0:3]
	s_setprio 0
	s_barrier
; #define PG8_STAGE(bufoff, gbase, voff) do { _Pragma("unroll") for (int _i = 0; _i < 2; ++_i) \
;         __builtin_amdgcn_global_load_lds((const unsigned*)((const char*)(gbase) + (voff)[_i]), (PG8_LAS unsigned*)(lds + (bufoff) + ldsw + _i * 8192), 16, 0, 0); } while (0)
; #define PG8_LDA(dst, b, h) do { _Pragma("unroll") for (int m = 0; m < 4; ++m) _Pragma("unroll") for (int k = 0; k < 2; ++k) dst[m][k] = *(const PG8_LAS bf16x8*)(lds + PG8_SA(b, h) + aoff + m * 2048 + k * 1024); } while (0)
; #define PG8_LDB(dst, b, h) do { _Pragma("unroll") for (int n = 0; n < 2; ++n) _Pragma("unroll") for (int k = 0; k < 2; ++k) dst[n][k] = *(const PG8_LAS bf16x8*)(lds + PG8_SB(b, h) + boff + n * 2048 + k * 1024); } while (0)
; #define PG8_MMA(ai, bj, At, Bt) do { __builtin_amdgcn_s_setprio(1); _Pragma("unroll") for (int m = 0; m < 4; ++m) _Pragma("unroll") for (int n = 0; n < 2; ++n) _Pragma("unroll") for (int k = 0; k < 2; ++k) \
;         acc[ai][bj][m][n] = __builtin_amdgcn_mfma_f32_16x16x32_bf16(Bt[n][k], At[m][k], acc[ai][bj][m][n], 0, 0, 0); __builtin_amdgcn_s_setprio(0); } while (0)
; #define PG8_WAIT_V(n) asm volatile("s_waitcnt vmcnt(" #n ")" ::: "memory")
; #define PG8_WAIT_L(n) asm volatile("s_waitcnt lgkmcnt(" #n ")" ::: "memory")
; #define PG8_BAR __builtin_amdgcn_s_barrier()
; #define PG8_SCHED __builtin_amdgcn_sched_barrier(0)
; template <class Epi, class Sched, bool ALIGN_EPI = false, bool SP2 = false>
; __device__ __forceinline__ void gemm_phase(PG8_LAS unsigned char* lds, const Gemm g, const Sched& S, const Epi& E) {
;     ...
;             PG8_LDB(B0, 1, 0); PG8_LDB(B1, 1, 1); PG8_SCHED; PG8_LDA(At, 1, 0); PG8_STAGE(PG8_SA(0, 1), a2 + hstep, voffA);
;             PG8_WAIT_V(8); PG8_WAIT_L(0); PG8_BAR; PG8_MMA(0, 0, At, B0); PG8_MMA(0, 1, At, B1); PG8_BAR; PG8_SCHED;
	s_add_i32 s52, 0, 0x18000
	v_add_u32_e32 v136, s52, v161
	s_add_i32 s53, 0, 0x1c000
	ds_read_b128 v[148:151], v136
	ds_read_b128 v[152:155], v136 offset:1024
	ds_read_b128 v[156:159], v136 offset:2048
	ds_read_b128 v[168:171], v136 offset:3072
	v_add_u32_e32 v136, s53, v161
	ds_read_b128 v[172:175], v136
	ds_read_b128 v[176:179], v136 offset:1024
	ds_read_b128 v[180:183], v136 offset:2048
	ds_read_b128 v[184:187], v136 offset:3072
	s_add_u32 s74, s74, 0x80000
	s_addc_u32 s75, s75, 0
	s_mov_b32 m0, s77
	v_lshl_add_u64 v[228:229], s[74:75], 0, v[134:135]
	ds_read_b128 v[188:191], v166 offset:32768
	ds_read_b128 v[192:195], v166 offset:33792
	ds_read_b128 v[196:199], v166 offset:34816
	ds_read_b128 v[200:203], v166 offset:35840
	ds_read_b128 v[204:207], v166 offset:36864
	ds_read_b128 v[208:211], v166 offset:37888
	ds_read_b128 v[212:215], v166 offset:38912
	ds_read_b128 v[216:219], v166 offset:39936
	global_load_lds_dwordx4 v[228:229], off
	v_lshl_add_u64 v[228:229], s[74:75], 0, v[130:131]
	s_mov_b32 m0, s78
	s_nop 0
	global_load_lds_dwordx4 v[228:229], off
	s_waitcnt lgkmcnt(0)
	s_barrier
	s_setprio 1
	s_waitcnt lgkmcnt(0)
	v_mfma_f32_16x16x32_bf16 v[124:127], v[148:151], v[188:191], v[124:127]
	v_mfma_f32_16x16x32_bf16 v[120:123], v[156:159], v[188:191], v[120:123]
	v_mfma_f32_16x16x32_bf16 v[116:119], v[148:151], v[196:199], v[116:119]
	v_mfma_f32_16x16x32_bf16 v[108:111], v[156:159], v[196:199], v[108:111]
	v_mfma_f32_16x16x32_bf16 v[100:103], v[148:151], v[204:207], v[100:103]
	v_mfma_f32_16x16x32_bf16 v[92:95], v[156:159], v[204:207], v[92:95]
	v_mfma_f32_16x16x32_bf16 v[84:87], v[148:151], v[212:215], v[84:87]
	v_mfma_f32_16x16x32_bf16 v[76:79], v[156:159], v[212:215], v[76:79]
	v_mfma_f32_16x16x32_bf16 v[124:127], v[152:155], v[192:195], v[124:127]
	v_mfma_f32_16x16x32_bf16 v[120:123], v[168:171], v[192:195], v[120:123]
	v_mfma_f32_16x16x32_bf16 v[116:119], v[152:155], v[200:203], v[116:119]
	v_mfma_f32_16x16x32_bf16 v[108:111], v[168:171], v[200:203], v[108:111]
	v_mfma_f32_16x16x32_bf16 v[100:103], v[152:155], v[208:211], v[100:103]
	v_mfma_f32_16x16x32_bf16 v[92:95], v[168:171], v[208:211], v[92:95]
	v_mfma_f32_16x16x32_bf16 v[84:87], v[152:155], v[216:219], v[84:87]
	v_mfma_f32_16x16x32_bf16 v[76:79], v[168:171], v[216:219], v[76:79]
	s_setprio 0
	s_setprio 1
	v_mfma_f32_16x16x32_bf16 v[112:115], v[172:175], v[188:191], v[112:115]
	v_mfma_f32_16x16x32_bf16 v[104:107], v[180:183], v[188:191], v[104:107]
	v_mfma_f32_16x16x32_bf16 v[96:99], v[172:175], v[196:199], v[96:99]
	v_mfma_f32_16x16x32_bf16 v[88:91], v[180:183], v[196:199], v[88:91]
	v_mfma_f32_16x16x32_bf16 v[80:83], v[172:175], v[204:207], v[80:83]
	v_mfma_f32_16x16x32_bf16 v[72:75], v[180:183], v[204:207], v[72:75]
	v_mfma_f32_16x16x32_bf16 v[68:71], v[172:175], v[212:215], v[68:71]
	v_mfma_f32_16x16x32_bf16 v[64:67], v[180:183], v[212:215], v[64:67]
	v_mfma_f32_16x16x32_bf16 v[112:115], v[176:179], v[192:195], v[112:115]
	v_mfma_f32_16x16x32_bf16 v[104:107], v[184:187], v[192:195], v[104:107]
	v_mfma_f32_16x16x32_bf16 v[96:99], v[176:179], v[200:203], v[96:99]
	v_mfma_f32_16x16x32_bf16 v[88:91], v[184:187], v[200:203], v[88:91]
	v_mfma_f32_16x16x32_bf16 v[80:83], v[176:179], v[208:211], v[80:83]
	v_mfma_f32_16x16x32_bf16 v[72:75], v[184:187], v[208:211], v[72:75]
	v_mfma_f32_16x16x32_bf16 v[68:71], v[176:179], v[216:219], v[68:71]
	v_mfma_f32_16x16x32_bf16 v[64:67], v[184:187], v[216:219], v[64:67]
	s_setprio 0
	s_barrier
; #define PG8_STAGE(bufoff, gbase, voff) do { _Pragma("unroll") for (int _i = 0; _i < 2; ++_i) \
;         __builtin_amdgcn_global_load_lds((const unsigned*)((const char*)(gbase) + (voff)[_i]), (PG8_LAS unsigned*)(lds + (bufoff) + ldsw + _i * 8192), 16, 0, 0); } while (0)
; #define PG8_LDA(dst, b, h) do { _Pragma("unroll") for (int m = 0; m < 4; ++m) _Pragma("unroll") for (int k = 0; k < 2; ++k) dst[m][k] = *(const PG8_LAS bf16x8*)(lds + PG8_SA(b, h) + aoff + m * 2048 + k * 1024); } while (0)
; #define PG8_MMA(ai, bj, At, Bt) do { __builtin_amdgcn_s_setprio(1); _Pragma("unroll") for (int m = 0; m < 4; ++m) _Pragma("unroll") for (int n = 0; n < 2; ++n) _Pragma("unroll") for (int k = 0; k < 2; ++k) \
;         acc[ai][bj][m][n] = __builtin_amdgcn_mfma_f32_16x16x32_bf16(Bt[n][k], At[m][k], acc[ai][bj][m][n], 0, 0, 0); __builtin_amdgcn_s_setprio(0); } while (0)
; #define PG8_WAIT_V(n) asm volatile("s_waitcnt vmcnt(" #n ")" ::: "memory")
; #define PG8_WAIT_L(n) asm volatile("s_waitcnt lgkmcnt(" #n ")" ::: "memory")
; #define PG8_BAR __builtin_amdgcn_s_barrier()
; #define PG8_SCHED __builtin_amdgcn_sched_barrier(0)
; template <class Epi, class Sched, bool ALIGN_EPI = false, bool SP2 = false>
; __device__ __forceinline__ void gemm_phase(PG8_LAS unsigned char* lds, const Gemm g, const Sched& S, const Epi& E) {
;     ...
;             PG8_LDA(At, 1, 1); PG8_STAGE(PG8_SB(1, 0), b3, voffB); PG8_STAGE(PG8_SB(1, 1), b3 + hstep, voffB); PG8_STAGE(PG8_SA(1, 0), a3, voffA);
;             PG8_WAIT_V(8); PG8_WAIT_L(0); PG8_BAR; PG8_MMA(1, 0, At, B0); PG8_MMA(1, 1, At, B1); PG8_BAR; PG8_SCHED;
	s_add_i32 s52, s52, s3
	v_lshl_add_u64 v[220:221], v[220:221], 0, s[12:13]
	s_mov_b32 m0, s52
	ds_read_b128 v[188:191], v166 offset:49152
	ds_read_b128 v[192:195], v166 offset:50176
	ds_read_b128 v[196:199], v166 offset:51200
	ds_read_b128 v[200:203], v166 offset:52224
	ds_read_b128 v[204:207], v166 offset:53248
	ds_read_b128 v[208:211], v166 offset:54272
	ds_read_b128 v[212:215], v166 offset:55296
	ds_read_b128 v[216:219], v166 offset:56320
	global_load_lds_dwordx4 v[220:221], off
	s_add_i32 m0, s52, 0x2000
	s_add_u32 s72, s72, 0x80080
	v_lshl_add_u64 v[220:221], v[222:223], 0, s[12:13]
	s_addc_u32 s73, s73, 0
	s_add_i32 s52, s53, s3
	global_load_lds_dwordx4 v[220:221], off
	v_lshl_add_u64 v[220:221], s[72:73], 0, v[132:133]
	s_mov_b32 m0, s52
	s_nop 0
	global_load_lds_dwordx4 v[220:221], off
	v_lshl_add_u64 v[220:221], s[72:73], 0, v[128:129]
	s_add_i32 m0, s52, 0x2000
	s_nop 0
	global_load_lds_dwordx4 v[220:221], off
	v_lshl_add_u64 v[220:221], v[224:225], 0, s[12:13]
	s_mov_b32 m0, s80
	s_nop 0
	global_load_lds_dwordx4 v[220:221], off
	v_lshl_add_u64 v[220:221], v[226:227], 0, s[12:13]
	s_mov_b32 m0, s81
	s_nop 0
	global_load_lds_dwordx4 v[220:221], off
	s_waitcnt vmcnt(8)
	s_waitcnt lgkmcnt(0)
	s_barrier
	s_setprio 1
	s_waitcnt lgkmcnt(0)
	v_mfma_f32_16x16x32_bf16 v[60:63], v[148:151], v[188:191], v[60:63]
	v_mfma_f32_16x16x32_bf16 v[56:59], v[156:159], v[188:191], v[56:59]
	v_mfma_f32_16x16x32_bf16 v[52:55], v[148:151], v[196:199], v[52:55]
	v_mfma_f32_16x16x32_bf16 v[44:47], v[156:159], v[196:199], v[44:47]
	v_mfma_f32_16x16x32_bf16 v[36:39], v[148:151], v[204:207], v[36:39]
	v_mfma_f32_16x16x32_bf16 v[28:31], v[156:159], v[204:207], v[28:31]
	v_mfma_f32_16x16x32_bf16 v[20:23], v[148:151], v[212:215], v[20:23]
	v_mfma_f32_16x16x32_bf16 v[12:15], v[156:159], v[212:215], v[12:15]
	v_mfma_f32_16x16x32_bf16 v[60:63], v[152:155], v[192:195], v[60:63]
	v_mfma_f32_16x16x32_bf16 v[56:59], v[168:171], v[192:195], v[56:59]
	v_mfma_f32_16x16x32_bf16 v[52:55], v[152:155], v[200:203], v[52:55]
	v_mfma_f32_16x16x32_bf16 v[44:47], v[168:171], v[200:203], v[44:47]
	v_mfma_f32_16x16x32_bf16 v[36:39], v[152:155], v[208:211], v[36:39]
	v_mfma_f32_16x16x32_bf16 v[28:31], v[168:171], v[208:211], v[28:31]
	v_mfma_f32_16x16x32_bf16 v[20:23], v[152:155], v[216:219], v[20:23]
	v_mfma_f32_16x16x32_bf16 v[12:15], v[168:171], v[216:219], v[12:15]
	s_setprio 0
	s_setprio 1
	v_mfma_f32_16x16x32_bf16 v[48:51], v[172:175], v[188:191], v[48:51]
	v_mfma_f32_16x16x32_bf16 v[40:43], v[180:183], v[188:191], v[40:43]
	v_mfma_f32_16x16x32_bf16 v[32:35], v[172:175], v[196:199], v[32:35]
	v_mfma_f32_16x16x32_bf16 v[24:27], v[180:183], v[196:199], v[24:27]
	v_mfma_f32_16x16x32_bf16 v[16:19], v[172:175], v[204:207], v[16:19]
	v_mfma_f32_16x16x32_bf16 v[8:11], v[180:183], v[204:207], v[8:11]
	v_mfma_f32_16x16x32_bf16 v[4:7], v[172:175], v[212:215], v[4:7]
	v_mfma_f32_16x16x32_bf16 v[0:3], v[180:183], v[212:215], v[0:3]
	v_mfma_f32_16x16x32_bf16 v[48:51], v[176:179], v[192:195], v[48:51]
	v_mfma_f32_16x16x32_bf16 v[40:43], v[184:187], v[192:195], v[40:43]
	v_mfma_f32_16x16x32_bf16 v[32:35], v[176:179], v[200:203], v[32:35]
	v_mfma_f32_16x16x32_bf16 v[24:27], v[184:187], v[200:203], v[24:27]
	v_mfma_f32_16x16x32_bf16 v[16:19], v[176:179], v[208:211], v[16:19]
	v_mfma_f32_16x16x32_bf16 v[8:11], v[184:187], v[208:211], v[8:11]
	v_mfma_f32_16x16x32_bf16 v[4:7], v[176:179], v[216:219], v[4:7]
	v_mfma_f32_16x16x32_bf16 v[0:3], v[184:187], v[216:219], v[0:3]
	s_setprio 0
	s_barrier
	s_add_i32 s93, s93, 2
	s_add_u32 s70, s70, 0x100
	s_addc_u32 s71, s71, 0
	s_add_u32 s91, s91, 0x100
	s_addc_u32 s92, s92, 0

;     __device__ __forceinline__ void operator()(const f32x4 (&acc)[2][2][4][2], const Unit& u, int wr, int wc, int fr, int fq) const {
;         const int row0 = u.pm * BM + wr * 64 + fr;
;         if (u.pn < 8) {
;             const int col0 = u.pn * BM + wc * 32 + 8 * fq;
; template <class Epi, class Sched, bool ALIGN_EPI = false, bool SP2 = false>
; __device__ __forceinline__ void gemm_phase(PG8_LAS unsigned char* lds, const Gemm g, const Sched& S, const Epi& E) {
;     ...
;         const char* nA = has_next ? PG8_UA(nxt) : cA; const char* nB = has_next ? PG8_UB(nxt) : cB;
.LBB0_203:
	s_add_u32 s100, s69, 0x80080
	s_addc_u32 s101, s39, 0
	v_lshl_add_u64 v[220:221], s[100:101], 0, v[138:139]
	s_add_i32 m0, s33, 0xc000
	s_nop 0
	global_load_lds_dwordx4 v[220:221], off
	v_lshl_add_u64 v[220:221], s[100:101], 0, v[140:141]
	s_add_i32 m0, s33, 0xe000
	s_nop 0
	global_load_lds_dwordx4 v[220:221], off
	v_lshl_add_u32 v148, s68, 8, v160
	v_ashrrev_i32_e32 v149, 31, v148
	v_or_b32_e32 v154, 16, v148
	v_or_b32_e32 v152, 32, v148
	v_or_b32_e32 v150, 48, v148
	s_cmp_gt_i32 s89, 7
	v_lshlrev_b64 v[156:157], 12, v[148:149]
	s_mov_b64 s[68:69], -1
	v_ashrrev_i32_e32 v155, 31, v154
	v_ashrrev_i32_e32 v153, 31, v152
	v_ashrrev_i32_e32 v151, 31, v150
	s_cbranch_scc1 .LBB0_206
	s_andn2_b64 vcc, exec, s[68:69]
	s_cbranch_vccz .LBB0_207

; __device__ __forceinline__ unsigned cvt_pk_bf16(float lo, float hi) { unsigned r; asm volatile("v_cvt_pk_bf16_f32 %0, %1, %2" : "=v"(r) : "v"(lo), "v"(hi)); return r; }
;     __device__ __forceinline__ void operator()(const f32x4 (&acc)[2][2][4][2], const Unit& u, int wr, int wc, int fr, int fq) const {
;     ...
;             const int col0 = (u.pn - 8) * HALF + wc * 32 + 8 * fq;
; #pragma unroll
;             for (int ai = 0; ai < 2; ++ai)
; #pragma unroll
;                 for (int m = 0; m < 4; ++m) { bf16_t* rowp = Zb + (size_t)(row0 + ai * HALF + m * 16) * D + col0;
;                     const f32x4 v0 = acc[ai][0][m][0] * acc[ai][1][m][0], v1 = acc[ai][0][m][1] * acc[ai][1][m][1];
;                     u32x4 w; w.x = cvt_pk_bf16(v0[0], v0[1]); w.y = cvt_pk_bf16(v0[2], v0[3]); w.z = cvt_pk_bf16(v1[0], v1[1]); w.w = cvt_pk_bf16(v1[2], v1[3]);
;                     *(u32x4*)rowp = w; }
.LBB0_206:
	v_lshl_add_u32 v136, s89, 7, v163
	v_lshl_add_u64 v[158:159], s[4:5], 0, v[156:157]
	v_lshlrev_b64 v[172:173], 1, v[136:137]
	v_pk_mul_f32 v[168:169], v[112:113], v[124:125]
	v_lshl_add_u64 v[158:159], v[158:159], 0, v[172:173]
	v_pk_mul_f32 v[170:171], v[114:115], v[126:127]
	v_cvt_pk_bf16_f32 v168, v168, v169
	v_pk_mul_f32 v[174:175], v[106:107], v[122:123]
	v_cvt_pk_bf16_f32 v169, v170, v171
	v_pk_mul_f32 v[176:177], v[104:105], v[120:121]
	v_pk_mul_f32 v[178:179], v[88:89], v[108:109]
	v_cvt_pk_bf16_f32 v170, v176, v177
	v_cvt_pk_bf16_f32 v171, v174, v175
	global_store_dwordx4 v[158:159], v[168:171], off
	v_pk_mul_f32 v[176:177], v[90:91], v[110:111]
	s_nop 0
	v_lshlrev_b64 v[168:169], 12, v[154:155]
	v_lshl_add_u64 v[168:169], s[4:5], 0, v[168:169]
	v_lshl_add_u64 v[174:175], v[168:169], 0, v[172:173]
	v_pk_mul_f32 v[168:169], v[96:97], v[116:117]
	v_pk_mul_f32 v[170:171], v[98:99], v[118:119]
	v_cvt_pk_bf16_f32 v168, v168, v169
	s_nop 0
	v_cvt_pk_bf16_f32 v169, v170, v171
	v_cvt_pk_bf16_f32 v170, v178, v179
	v_cvt_pk_bf16_f32 v171, v176, v177
	global_store_dwordx4 v[174:175], v[168:171], off
	v_pk_mul_f32 v[176:177], v[74:75], v[94:95]
	v_pk_mul_f32 v[178:179], v[72:73], v[92:93]
	v_lshlrev_b64 v[168:169], 12, v[152:153]
	v_lshl_add_u64 v[168:169], s[4:5], 0, v[168:169]
	v_lshl_add_u64 v[174:175], v[168:169], 0, v[172:173]
	v_pk_mul_f32 v[168:169], v[80:81], v[100:101]
	v_pk_mul_f32 v[170:171], v[82:83], v[102:103]
	v_cvt_pk_bf16_f32 v168, v168, v169
	s_nop 0
	v_cvt_pk_bf16_f32 v169, v170, v171
	v_cvt_pk_bf16_f32 v170, v178, v179
	v_cvt_pk_bf16_f32 v171, v176, v177
	global_store_dwordx4 v[174:175], v[168:171], off
	v_pk_mul_f32 v[174:175], v[66:67], v[78:79]
	v_pk_mul_f32 v[176:177], v[64:65], v[76:77]
	v_lshlrev_b64 v[168:169], 12, v[150:151]
	v_lshl_add_u64 v[168:169], s[4:5], 0, v[168:169]
	v_lshl_add_u64 v[172:173], v[168:169], 0, v[172:173]
	v_pk_mul_f32 v[170:171], v[70:71], v[86:87]
	v_pk_mul_f32 v[168:169], v[68:69], v[84:85]
	s_nop 0
	v_cvt_pk_bf16_f32 v168, v168, v169
	v_cvt_pk_bf16_f32 v169, v170, v171
	v_cvt_pk_bf16_f32 v170, v176, v177
	v_cvt_pk_bf16_f32 v171, v174, v175
	global_store_dwordx4 v[172:173], v[168:171], off
	v_pk_mul_f32 v[172:173], v[42:43], v[58:59]
	v_pk_mul_f32 v[174:175], v[40:41], v[56:57]
	v_pk_mul_f32 v[170:171], v[50:51], v[62:63]
	v_pk_mul_f32 v[168:169], v[48:49], v[60:61]
	s_nop 0
	v_cvt_pk_bf16_f32 v168, v168, v169
	v_cvt_pk_bf16_f32 v169, v170, v171
	v_cvt_pk_bf16_f32 v170, v174, v175
	v_cvt_pk_bf16_f32 v171, v172, v173
	v_add_co_u32_e32 v172, vcc, s86, v158
	v_pk_mul_f32 v[174:175], v[24:25], v[44:45]
	s_nop 0
	v_addc_co_u32_e32 v173, vcc, 0, v159, vcc
	global_store_dwordx4 v[172:173], v[168:171], off
	v_pk_mul_f32 v[172:173], v[26:27], v[46:47]
	s_nop 0
	v_pk_mul_f32 v[170:171], v[34:35], v[54:55]
	v_pk_mul_f32 v[168:169], v[32:33], v[52:53]
	s_nop 0
	v_cvt_pk_bf16_f32 v168, v168, v169
	v_cvt_pk_bf16_f32 v169, v170, v171
	v_cvt_pk_bf16_f32 v170, v174, v175
	v_cvt_pk_bf16_f32 v171, v172, v173
	v_add_co_u32_e32 v172, vcc, s87, v158
	v_pk_mul_f32 v[174:175], v[8:9], v[28:29]
	s_nop 0
	v_addc_co_u32_e32 v173, vcc, 0, v159, vcc
	global_store_dwordx4 v[172:173], v[168:171], off
	v_pk_mul_f32 v[172:173], v[10:11], v[30:31]
	s_nop 0
	v_pk_mul_f32 v[170:171], v[18:19], v[38:39]
	v_pk_mul_f32 v[168:169], v[16:17], v[36:37]
	s_nop 0
	v_cvt_pk_bf16_f32 v168, v168, v169
	v_cvt_pk_bf16_f32 v169, v170, v171
	v_cvt_pk_bf16_f32 v170, v174, v175
	v_cvt_pk_bf16_f32 v171, v172, v173
	v_add_co_u32_e32 v172, vcc, s88, v158
	v_pk_mul_f32 v[174:175], v[0:1], v[12:13]
	s_nop 0
	v_addc_co_u32_e32 v173, vcc, 0, v159, vcc
	v_add_co_u32_e32 v158, vcc, 0xb0000, v158
	global_store_dwordx4 v[172:173], v[168:171], off
	s_nop 0
	v_addc_co_u32_e32 v159, vcc, 0, v159, vcc
	v_pk_mul_f32 v[170:171], v[6:7], v[22:23]
	v_pk_mul_f32 v[168:169], v[4:5], v[20:21]
	v_pk_mul_f32 v[172:173], v[2:3], v[14:15]
	v_cvt_pk_bf16_f32 v168, v168, v169
	v_cvt_pk_bf16_f32 v169, v170, v171
	v_cvt_pk_bf16_f32 v170, v174, v175
	s_nop 0
	v_cvt_pk_bf16_f32 v171, v172, v173
	global_store_dwordx4 v[158:159], v[168:171], off
	s_waitcnt vmcnt(8)
	s_cbranch_execnz .LBB0_205
; __device__ __forceinline__ unsigned cvt_pk_bf16(float lo, float hi) { unsigned r; asm volatile("v_cvt_pk_bf16_f32 %0, %1, %2" : "=v"(r) : "v"(lo), "v"(hi)); return r; }
;     __device__ __forceinline__ void operator()(const f32x4 (&acc)[2][2][4][2], const Unit& u, int wr, int wc, int fr, int fq) const {
;     ...
;             const int col0 = u.pn * BM + wc * 32 + 8 * fq;
; #pragma unroll
;             for (int ai = 0; ai < 2; ++ai)
; #pragma unroll
;                 for (int m = 0; m < 4; ++m) { bf16_t* rowp = Bb + (size_t)(row0 + ai * HALF + m * 16) * D + col0;
; #pragma unroll
;                     for (int bj = 0; bj < 2; ++bj) { const f32x4 v0 = acc[ai][bj][m][0], v1 = acc[ai][bj][m][1];
;                         u32x4 w; w.x = cvt_pk_bf16(v0[0], v0[1]); w.y = cvt_pk_bf16(v0[2], v0[3]); w.z = cvt_pk_bf16(v1[0], v1[1]); w.w = cvt_pk_bf16(v1[2], v1[3]);
;                         *(u32x4*)(rowp + bj * HALF) = w; } }
.LBB0_207:
	v_lshl_or_b32 v158, s89, 8, v162
	v_ashrrev_i32_e32 v159, 31, v158
	v_lshl_add_u64 v[156:157], s[16:17], 0, v[156:157]
	v_lshlrev_b64 v[158:159], 1, v[158:159]
	v_lshl_add_u64 v[156:157], v[156:157], 0, v[158:159]
	v_cvt_pk_bf16_f32 v124, v124, v125
	v_cvt_pk_bf16_f32 v125, v126, v127
	v_cvt_pk_bf16_f32 v126, v120, v121
	v_cvt_pk_bf16_f32 v127, v122, v123
	global_store_dwordx4 v[156:157], v[124:127], off
	v_cvt_pk_bf16_f32 v112, v112, v113
	v_cvt_pk_bf16_f32 v113, v114, v115
	v_cvt_pk_bf16_f32 v114, v104, v105
	v_lshlrev_b64 v[104:105], 12, v[154:155]
	v_lshl_add_u64 v[104:105], s[16:17], 0, v[104:105]
	v_cvt_pk_bf16_f32 v115, v106, v107
	global_store_dwordx4 v[156:157], v[112:115], off offset:256
	s_mov_b64 s[68:69], 0x80000
	s_mov_b32 s35, 0xb0000
	v_lshl_add_u64 v[112:113], v[104:105], 0, v[158:159]
	v_cvt_pk_bf16_f32 v104, v116, v117
	v_cvt_pk_bf16_f32 v105, v118, v119
	v_cvt_pk_bf16_f32 v106, v108, v109
	v_cvt_pk_bf16_f32 v107, v110, v111
	global_store_dwordx4 v[112:113], v[104:107], off
	v_cvt_pk_bf16_f32 v96, v96, v97
	v_cvt_pk_bf16_f32 v97, v98, v99
	v_cvt_pk_bf16_f32 v98, v88, v89
	v_lshlrev_b64 v[88:89], 12, v[152:153]
	v_lshl_add_u64 v[88:89], s[16:17], 0, v[88:89]
	v_cvt_pk_bf16_f32 v99, v90, v91
	global_store_dwordx4 v[112:113], v[96:99], off offset:256
	s_nop 1
	v_lshl_add_u64 v[96:97], v[88:89], 0, v[158:159]
	v_cvt_pk_bf16_f32 v88, v100, v101
	v_cvt_pk_bf16_f32 v89, v102, v103
	v_cvt_pk_bf16_f32 v90, v92, v93
	v_cvt_pk_bf16_f32 v91, v94, v95
	global_store_dwordx4 v[96:97], v[88:91], off
	v_cvt_pk_bf16_f32 v80, v80, v81
	v_cvt_pk_bf16_f32 v81, v82, v83
	v_cvt_pk_bf16_f32 v82, v72, v73
	v_lshlrev_b64 v[72:73], 12, v[150:151]
	v_lshl_add_u64 v[72:73], s[16:17], 0, v[72:73]
	v_cvt_pk_bf16_f32 v83, v74, v75
	global_store_dwordx4 v[96:97], v[80:83], off offset:256
	s_nop 1
	v_lshl_add_u64 v[80:81], v[72:73], 0, v[158:159]
	v_cvt_pk_bf16_f32 v72, v84, v85
	v_cvt_pk_bf16_f32 v73, v86, v87
	v_cvt_pk_bf16_f32 v74, v76, v77
	v_cvt_pk_bf16_f32 v75, v78, v79
	global_store_dwordx4 v[80:81], v[72:75], off
	v_cvt_pk_bf16_f32 v68, v68, v69
	v_cvt_pk_bf16_f32 v69, v70, v71
	v_cvt_pk_bf16_f32 v70, v64, v65
	v_lshlrev_b64 v[64:65], 12, v[148:149]
	v_lshl_add_u64 v[64:65], s[16:17], 0, v[64:65]
	v_lshl_add_u64 v[64:65], v[64:65], 0, v[158:159]
	v_cvt_pk_bf16_f32 v71, v66, v67
	global_store_dwordx4 v[80:81], v[68:71], off offset:256
	v_cvt_pk_bf16_f32 v60, v60, v61
	v_cvt_pk_bf16_f32 v61, v62, v63
	v_cvt_pk_bf16_f32 v62, v56, v57
	v_add_co_u32_e32 v56, vcc, s86, v64
	v_lshl_add_u64 v[66:67], v[64:65], 0, s[68:69]
	s_nop 0
	v_addc_co_u32_e32 v57, vcc, 0, v65, vcc
	v_cvt_pk_bf16_f32 v63, v58, v59
	global_store_dwordx4 v[56:57], v[60:63], off
	v_cvt_pk_bf16_f32 v48, v48, v49
	v_cvt_pk_bf16_f32 v49, v50, v51
	v_cvt_pk_bf16_f32 v50, v40, v41
	v_cvt_pk_bf16_f32 v51, v42, v43
	global_store_dwordx4 v[66:67], v[48:51], off offset:256
	s_mov_b64 s[68:69], 0x90000
	v_cvt_pk_bf16_f32 v40, v52, v53
	v_cvt_pk_bf16_f32 v41, v54, v55
	v_cvt_pk_bf16_f32 v42, v44, v45
	v_add_co_u32_e32 v44, vcc, s87, v64
	v_lshl_add_u64 v[48:49], v[64:65], 0, s[68:69]
	s_nop 0
	v_addc_co_u32_e32 v45, vcc, 0, v65, vcc
	v_cvt_pk_bf16_f32 v43, v46, v47
	global_store_dwordx4 v[44:45], v[40:43], off
	v_cvt_pk_bf16_f32 v32, v32, v33
	v_cvt_pk_bf16_f32 v33, v34, v35
	v_cvt_pk_bf16_f32 v34, v24, v25
	v_cvt_pk_bf16_f32 v35, v26, v27
	global_store_dwordx4 v[48:49], v[32:35], off offset:256
	s_mov_b64 s[68:69], 0xa0000
	v_cvt_pk_bf16_f32 v24, v36, v37
	v_cvt_pk_bf16_f32 v25, v38, v39
	v_cvt_pk_bf16_f32 v26, v28, v29
	v_add_co_u32_e32 v28, vcc, s88, v64
	v_lshl_add_u64 v[32:33], v[64:65], 0, s[68:69]
	s_nop 0
	v_addc_co_u32_e32 v29, vcc, 0, v65, vcc
	v_cvt_pk_bf16_f32 v27, v30, v31
	global_store_dwordx4 v[28:29], v[24:27], off
	v_cvt_pk_bf16_f32 v16, v16, v17
	v_cvt_pk_bf16_f32 v17, v18, v19
	v_cvt_pk_bf16_f32 v18, v8, v9
	v_cvt_pk_bf16_f32 v19, v10, v11
	global_store_dwordx4 v[32:33], v[16:19], off offset:256
	s_mov_b64 s[68:69], 0xb0000
	v_cvt_pk_bf16_f32 v8, v20, v21
	v_cvt_pk_bf16_f32 v9, v22, v23
	v_cvt_pk_bf16_f32 v10, v12, v13
	v_add_co_u32_e32 v12, vcc, s35, v64
	v_lshl_add_u64 v[16:17], v[64:65], 0, s[68:69]
	s_nop 0
	v_addc_co_u32_e32 v13, vcc, 0, v65, vcc
	v_cvt_pk_bf16_f32 v11, v14, v15
	global_store_dwordx4 v[12:13], v[8:11], off
	v_cvt_pk_bf16_f32 v4, v4, v5
	v_cvt_pk_bf16_f32 v5, v6, v7
	v_cvt_pk_bf16_f32 v6, v0, v1
	v_cvt_pk_bf16_f32 v7, v2, v3
	global_store_dwordx4 v[16:17], v[4:7], off offset:256
	s_waitcnt vmcnt(16)
	s_andn2_b64 vcc, exec, s[0:1]
	s_mov_b64 s[0:1], -1
	s_cbranch_vccnz .LBB0_196

; __global__ void __launch_bounds__(NTHREADS, 2) fwd_megakernel(Args args) {
	.amdhsa_kernel _Z14fwd_megakernel4Args
		.amdhsa_group_segment_fixed_size 0
		.amdhsa_private_segment_fixed_size 0
		.amdhsa_kernarg_size 416
		.amdhsa_user_sgpr_count 2
		.amdhsa_user_sgpr_dispatch_ptr 0
		.amdhsa_user_sgpr_queue_ptr 0
		.amdhsa_user_sgpr_kernarg_segment_ptr 1
		.amdhsa_user_sgpr_dispatch_id 0
		.amdhsa_user_sgpr_kernarg_preload_length 0
		.amdhsa_user_sgpr_kernarg_preload_offset 0
		.amdhsa_user_sgpr_private_segment_size 0
		.amdhsa_uses_dynamic_stack 0
		.amdhsa_enable_private_segment 0
		.amdhsa_system_sgpr_workgroup_id_x 1
		.amdhsa_system_sgpr_workgroup_id_y 0
		.amdhsa_system_sgpr_workgroup_id_z 0
		.amdhsa_system_sgpr_workgroup_info 0
		.amdhsa_system_vgpr_workitem_id 2
		.amdhsa_next_free_vgpr 256
		.amdhsa_next_free_sgpr 102
		.amdhsa_accum_offset 256
		.amdhsa_reserve_vcc 1
		.amdhsa_float_round_mode_32 0
		.amdhsa_float_round_mode_16_64 0
		.amdhsa_float_denorm_mode_32 3
		.amdhsa_float_denorm_mode_16_64 3
		.amdhsa_dx10_clamp 1
		.amdhsa_ieee_mode 1
		.amdhsa_fp16_overflow 0
		.amdhsa_tg_split 0
		.amdhsa_exception_fp_ieee_invalid_op 0
		.amdhsa_exception_fp_denorm_src 0
		.amdhsa_exception_fp_ieee_div_zero 0
		.amdhsa_exception_fp_ieee_overflow 0
		.amdhsa_exception_fp_ieee_underflow 0
		.amdhsa_exception_fp_ieee_inexact 0
		.amdhsa_exception_int_div_zero 0
	.end_amdhsa_kernel

; __global__ void __launch_bounds__(NTHREADS, 2) fwd_megakernel(Args args) {
amdhsa.kernels:
  - .agpr_count:     0
    .args:
      - .offset:         0
        .size:           160
        .value_kind:     by_value
      - .offset:         160
        .size:           4
        .value_kind:     hidden_block_count_x
      - .offset:         164
        .size:           4
        .value_kind:     hidden_block_count_y
      - .offset:         168
        .size:           4
        .value_kind:     hidden_block_count_z
      - .offset:         172
        .size:           2
        .value_kind:     hidden_group_size_x
      - .offset:         174
        .size:           2
        .value_kind:     hidden_group_size_y
      - .offset:         176
        .size:           2
        .value_kind:     hidden_group_size_z
      - .offset:         178
        .size:           2
        .value_kind:     hidden_remainder_x
      - .offset:         180
        .size:           2
        .value_kind:     hidden_remainder_y
      - .offset:         182
        .size:           2
        .value_kind:     hidden_remainder_z
      - .offset:         200
        .size:           8
        .value_kind:     hidden_global_offset_x
      - .offset:         208
        .size:           8
        .value_kind:     hidden_global_offset_y
      - .offset:         216
        .size:           8
        .value_kind:     hidden_global_offset_z
      - .offset:         224
        .size:           2
        .value_kind:     hidden_grid_dims
      - .offset:         248
        .size:           8
        .value_kind:     hidden_multigrid_sync_arg
      - .offset:         280
        .size:           4
        .value_kind:     hidden_dynamic_lds_size
    .group_segment_fixed_size: 0
    .kernarg_segment_align: 8
    .kernarg_segment_size: 416
    .language:       OpenCL C
    .language_version:
      - 2
      - 0
    .max_flat_workgroup_size: 512
    .name:           _Z14fwd_megakernel4Args
    .private_segment_fixed_size: 0
    .sgpr_count:     108
    .sgpr_spill_count: 19
    .symbol:         _Z14fwd_megakernel4Args.kd
    .uniform_work_group_size: 1
    .uses_dynamic_stack: false
    .vgpr_count:     256
    .vgpr_spill_count: 0
    .wavefront_size: 64
